# L1 invalidate issued on entering each panel / data-flow wait instead of after it
# speedup vs baseline: 1.0407x; 1.0093x over previous
; #define SEAM(k) do { if (IN(k) && IN((k) + 1)) xcd_barrier(bar); } while (0)
; __global__ void __launch_bounds__(NWAVES * 64, 2) mega_fwd(Args args) {
;     ...
;     SEAM(1);
;     if (IN(2)) { pg8::Gemm g{ACT, W1d, M, DM, FF, 64, FF, 0, 0, 1, (size_t)256 * 64 * 2, (size_t)(FF / 64) * 256 * 64 * 2}; pg8::StaticOrder S; S.init(M, DM, 1, G, bx);
;         pg8::EpiResid<true> E{nullptr, XB, ss1, 0.5f}; pg8::gemm_phase<pg8::EpiResid<true>, true>(lds, g, S, E); }
.LBB0_252:
	s_cmp_gt_i32 s85, 2
	s_cselect_b64 s[2:3], -1, 0
	s_and_b64 s[4:5], s[6:7], s[2:3]
	s_andn2_b64 vcc, exec, s[4:5]
	s_cbranch_vccnz .LBB0_306
	s_waitcnt vmcnt(0)
	s_barrier
	s_mov_b64 s[4:5], exec
	v_readlane_b32 s6, v251, 18
	v_readlane_b32 s7, v251, 19
	s_and_b64 s[6:7], s[4:5], s[6:7]
	s_mov_b64 exec, s[6:7]
	s_cbranch_execz .LBB0_305
	buffer_inv sc1
	s_and_b32 s10, s88, 7
	s_lshl_b32 s10, s10, 3
	s_bfe_u32 s11, s88, 0x30003
	s_or_b32 s10, s10, s11
	s_lshl_b32 s10, s10, 8
	s_add_u32 s12, s66, 0xfd09000
	s_addc_u32 s13, s67, 0
	v_mov_b32_e32 v1, s10
	v_mov_b32_e32 v2, 1
	global_atomic_add v1, v2, s[12:13]
	s_movk_i32 s11, 4
	s_mov_b32 s14, 0
.Lls1_spin:
	global_load_dword v3, v1, s[12:13] sc1
	v_mov_b32_e32 v5, 0x6000
	global_load_dword v6, v5, s[12:13] sc1
	s_waitcnt vmcnt(0)
	v_readfirstlane_b32 s15, v3
	v_readfirstlane_b32 s10, v6
	s_nop 3
	s_cmp_ge_u32 s15, s11
	s_cselect_b32 s15, 1, 0
	s_cmp_ge_u32 s10, 0x80
	s_cselect_b32 s10, 1, 0
	s_and_b32 s15, s15, s10
	s_cmp_lg_u32 s15, 0
	s_cbranch_scc1 .Lls1_ok
	s_sleep 1
	s_add_i32 s14, s14, 1
	s_cmp_lt_u32 s14, 0x20000
	s_cbranch_scc1 .Lls1_spin
.Lls1_ok:
	s_waitcnt vmcnt(0)
.LBB0_305:
	s_or_b64 exec, exec, s[4:5]
	s_waitcnt lgkmcnt(0)
	s_barrier

; #define SEAM(k) do { if (IN(k) && IN((k) + 1)) xcd_barrier(bar); } while (0)
; __global__ void __launch_bounds__(NWAVES * 64, 2) mega_fwd(Args args) {
;     ...
;     SEAM(2);
;     if (IN(3)) { pg8::Gemm g{XB, Win, M, NIN, DM, DM, DM, 0, 0, 1}; pg8::StaticOrder S; S.init(M, NIN, 1, G, bx);
.LBB0_353:
	s_cmp_gt_i32 s85, 3
	s_cselect_b64 s[2:3], -1, 0
	s_and_b64 s[4:5], s[10:11], s[2:3]
	s_andn2_b64 vcc, exec, s[4:5]
	s_cbranch_vccnz .LBB0_407
	s_waitcnt vmcnt(0)
	s_waitcnt lgkmcnt(0)
	s_barrier
	s_mov_b64 s[4:5], exec
	v_readlane_b32 s6, v251, 18
	v_readlane_b32 s7, v251, 19
	s_and_b64 s[6:7], s[4:5], s[6:7]
	s_mov_b64 exec, s[6:7]
	s_cbranch_execz .LBB0_406
	buffer_inv sc1
	s_and_b32 s10, s88, 7
	s_lshl_b32 s10, s10, 3
	s_bfe_u32 s11, s88, 0x30003
	s_or_b32 s10, s10, s11
	s_lshl_b32 s10, s10, 8
	s_add_u32 s12, s66, 0xfd09000
	s_addc_u32 s13, s67, 0
	v_mov_b32_e32 v1, s10
	v_mov_b32_e32 v2, 1
	global_atomic_add v1, v2, s[12:13]
	v_mov_b32_e32 v5, 0x5800
	global_atomic_add v5, v2, s[12:13]
	s_movk_i32 s11, 8
	s_mov_b32 s14, 0
.Lls2_spin:
	global_load_dword v3, v1, s[12:13] sc1
	s_waitcnt vmcnt(0)
	v_readfirstlane_b32 s15, v3
	s_nop 3
	s_cmp_ge_u32 s15, s11
	s_cbranch_scc1 .Lls2_ok
	s_sleep 1
	s_add_i32 s14, s14, 1
	s_cmp_lt_u32 s14, 0x20000
	s_cbranch_scc1 .Lls2_spin
.Lls2_ok:
	s_waitcnt vmcnt(0)
.LBB0_406:
	s_or_b64 exec, exec, s[4:5]
	s_waitcnt lgkmcnt(0)
	s_barrier

; #define SEAM(k) do { if (IN(k) && IN((k) + 1)) xcd_barrier(bar); } while (0)
; __global__ void __launch_bounds__(NWAVES * 64, 2) mega_fwd(Args args) {
;     ...
;     SEAM(6);
;     if (IN(7)) { pg8::Gemm g{ZB, Wglu, M, 512, 512, 512, 512, 0, 0, 1}; pg8::StaticOrder S; S.init(M, 512, 1, G, bx);
;         pg8::EpiGlu E{ZB, args.in[19], Z2B}; pg8::gemm_phase<pg8::EpiGlu, true>(lds, g, S, E); }
.LBB0_955:
	s_cmp_gt_i32 s85, 7
	s_cselect_b64 s[2:3], -1, 0
	s_and_b64 s[0:1], s[6:7], s[2:3]
	v_readlane_b32 s82, v252, 10
	s_andn2_b64 vcc, exec, s[0:1]
	v_readlane_b32 s83, v252, 11
	s_cbranch_vccnz .LBB0_1009
	s_cmpk_lt_i32 s88, 0x80
	s_cbranch_scc1 .LBB0_1009
	s_waitcnt vmcnt(0) lgkmcnt(0)
	s_barrier
	s_and_saveexec_b64 s[0:1], s[74:75]
	s_cbranch_execz .Lys_done
	buffer_wbl2 sc1
	s_waitcnt vmcnt(0)
	buffer_inv sc1
	v_readlane_b32 s4, v252, 26
	v_readlane_b32 s5, v252, 27
	v_mov_b32_e32 v1, 0x4000
	v_mov_b32_e32 v2, 1
	s_mov_b32 s6, 0
	s_nop 4
	global_atomic_add v1, v2, s[4:5]
.Lys_spin:
	global_load_dword v3, v1, s[4:5] sc1
	s_waitcnt vmcnt(0)
	v_readfirstlane_b32 s7, v3
	s_nop 3
	s_cmpk_ge_u32 s7, 0xc0
	s_cbranch_scc1 .Lys_ok
	s_sleep 2
	s_add_i32 s6, s6, 1
	s_cmp_lt_u32 s6, 0x20000
	s_cbranch_scc1 .Lys_spin
.Lys_ok:
	s_waitcnt vmcnt(0)
.Lys_done:
	s_or_b64 exec, exec, s[0:1]
	s_barrier

; #define SEAM(k) do { if (IN(k) && IN((k) + 1)) xcd_barrier(bar); } while (0)
; __global__ void __launch_bounds__(NWAVES * 64, 2) mega_fwd(Args args) {
;     ...
;     SEAM(7);
;     if (IN(8)) { pg8::StaticOrder S; S.init(M, DM, 1, G, bx);
;         { pg8::Gemm g{QB_, Wab, M, DM, 512, 512, 512, 0, 0, 1}; pg8::EpiBranch<false> E{(const unsigned char*)GATES, 0, MG}; pg8::gemm_phase<pg8::EpiBranch<false>, true>(lds, g, S, E); }
;         { pg8::Gemm g{Z2B, Wsb, M, DM, 512, 512, 512, 0, 0, 1}; pg8::EpiBranch<true> E{(const unsigned char*)GATES, 1024, MG}; pg8::gemm_phase<pg8::EpiBranch<true>, true>(lds, g, S, E); } }
.LBB0_1034:
	s_cmp_gt_i32 s85, 8
	s_cselect_b64 s[2:3], -1, 0
	s_and_b64 s[4:5], s[4:5], s[2:3]
	s_andn2_b64 vcc, exec, s[4:5]
	s_cbranch_vccnz .LBB0_1088
	s_waitcnt vmcnt(0)
	s_waitcnt vmcnt(0) lgkmcnt(0)
	s_barrier
	s_and_saveexec_b64 s[4:5], s[74:75]
	s_cbranch_execz .LBB0_1087
	buffer_inv sc1
	s_and_b32 s6, s88, 7
	s_lshl_b32 s6, s6, 3
	s_bfe_u32 s7, s88, 0x30003
	s_or_b32 s6, s6, s7
	s_lshl_b32 s6, s6, 6
	s_add_i32 s6, s6, 0xfd0d000
	v_mov_b32_e32 v1, s6
	v_mov_b32_e32 v2, 0xfd0ec00
	v_mov_b32_e32 v3, 0xfd08000
	s_mov_b32 s8, 0
.Ldf7_spin:
	global_load_dword v4, v1, s[66:67] sc1
	global_load_dword v5, v1, s[66:67] offset:32 sc1
	global_load_dword v6, v2, s[66:67] sc1
	global_load_dword v16, v3, s[66:67] sc1
	s_waitcnt vmcnt(0)
	v_readfirstlane_b32 s9, v4
	v_readfirstlane_b32 s10, v5
	v_readfirstlane_b32 s11, v6
	v_readfirstlane_b32 s12, v16
	s_nop 3
	s_cmp_ge_u32 s9, 8
	s_cselect_b32 s9, 1, 0
	s_cmp_ge_u32 s10, 2
	s_cselect_b32 s10, 1, 0
	s_cmp_ge_u32 s11, 64
	s_cselect_b32 s11, 1, 0
	s_cmp_ge_u32 s12, 0xc0
	s_cselect_b32 s12, 1, 0
	s_and_b32 s9, s9, s10
	s_and_b32 s11, s11, s12
	s_and_b32 s9, s9, s11
	s_cmp_lg_u32 s9, 0
	s_cbranch_scc1 .Ldf7_ok
	s_sleep 1
	s_add_i32 s8, s8, 1
	s_cmp_lt_u32 s8, 0x20000
	s_cbranch_scc1 .Ldf7_spin
.Ldf7_ok:
	s_waitcnt vmcnt(0)
.LBB0_1087:
	s_or_b64 exec, exec, s[4:5]
	s_waitcnt lgkmcnt(0)
	s_barrier

; #define SEAM(k) do { if (IN(k) && IN((k) + 1)) xcd_barrier(bar); } while (0)
; __global__ void __launch_bounds__(NWAVES * 64, 2) mega_fwd(Args args) {
;     ...
;     SEAM(8);
;     if (IN(9)) { pg8::Gemm g{MG, Wout, M, DM, DM, DM, DM, 0, 0, 1}; pg8::StaticOrder S; S.init(M, DM, 1, G, bx);
;         pg8::EpiResid<true> E{nullptr, XB, ss2, 1.0f}; pg8::gemm_phase<pg8::EpiResid<true>, true>(lds, g, S, E); }
.LBB0_1138:
	s_cmp_gt_i32 s85, 9
	s_cselect_b64 s[0:1], -1, 0
	s_and_b64 s[2:3], s[4:5], s[0:1]
	s_andn2_b64 vcc, exec, s[2:3]
	s_cbranch_vccnz .LBB0_1192
	s_waitcnt vmcnt(0)
	s_waitcnt vmcnt(0) lgkmcnt(0)
	s_barrier
	s_and_saveexec_b64 s[2:3], s[74:75]
	s_cbranch_execz .LBB0_1191
	buffer_inv sc1
	s_and_b32 s4, s88, 7
	s_lshl_b32 s4, s4, 3
	s_bfe_u32 s5, s88, 0x30003
	s_or_b32 s4, s4, s5
	s_lshl_b32 s4, s4, 8
	s_add_u32 s6, s66, 0xfd09000
	s_addc_u32 s7, s67, 0
	v_mov_b32_e32 v1, s4
	v_mov_b32_e32 v2, 1
	global_atomic_add v1, v2, s[6:7]
	v_mov_b32_e32 v5, 0x5000
	global_atomic_add v5, v2, s[6:7]
	s_movk_i32 s5, 12
	s_mov_b32 s8, 0
.Lls8_spin:
	global_load_dword v3, v1, s[6:7] sc1
	s_waitcnt vmcnt(0)
	v_readfirstlane_b32 s9, v3
	s_nop 3
	s_cmp_ge_u32 s9, s5
	s_cbranch_scc1 .Lls8_ok
	s_sleep 1
	s_add_i32 s8, s8, 1
	s_cmp_lt_u32 s8, 0x20000
	s_cbranch_scc1 .Lls8_spin
.Lls8_ok:
	s_waitcnt vmcnt(0)
.LBB0_1191:
	s_or_b64 exec, exec, s[2:3]
	s_waitcnt lgkmcnt(0)
	s_barrier

; #define SEAM(k) do { if (IN(k) && IN((k) + 1)) xcd_barrier(bar); } while (0)
; __global__ void __launch_bounds__(NWAVES * 64, 2) mega_fwd(Args args) {
;     ...
;     SEAM(9);
;     if (IN(10)) { pg8::Gemm g{XB, W2gu, M, 2 * FF, DM, DM, DM, 0, 0, 1}; pg8::StaticOrder S; S.init(M, 2 * FF, 1, G, bx);
;         pg8::EpiSwiglu E{ss2, ACT}; pg8::gemm_phase<pg8::EpiSwiglu, true>(lds, g, S, E);
;         if (bx >= 128) {
;             pg8::Gemm g2{PB, Wpp, M, DM, PLE, PLE, PLE, 0, 0, 1}; pg8::StaticOrder S2; S2.init(M, DM, 1, G - 128, bx - 128);
;             pg8::EpiPle1 E2{PTMP}; pg8::gemm_phase<pg8::EpiPle1, true>(lds, g2, S2, E2); } }
.LBB0_1235:
	s_cmp_gt_i32 s85, 10
	s_cselect_b64 s[2:3], -1, 0
	s_and_b64 s[0:1], s[0:1], s[2:3]
	s_andn2_b64 vcc, exec, s[0:1]
	s_cbranch_vccnz .LBB0_1289
	s_waitcnt vmcnt(0)
	s_waitcnt vmcnt(0) lgkmcnt(0)
	s_barrier
	s_and_saveexec_b64 s[0:1], s[74:75]
	s_cbranch_execz .LBB0_1288
	buffer_inv sc1
	s_and_b32 s4, s88, 7
	s_lshl_b32 s4, s4, 3
	s_bfe_u32 s5, s88, 0x30003
	s_or_b32 s4, s4, s5
	s_lshl_b32 s4, s4, 8
	s_add_u32 s6, s66, 0xfd09000
	s_addc_u32 s7, s67, 0
	v_mov_b32_e32 v1, s4
	v_mov_b32_e32 v2, 1
	global_atomic_add v1, v2, s[6:7]
	s_movk_i32 s5, 16
	s_mov_b32 s8, 0
.Lls9_spin:
	global_load_dword v3, v1, s[6:7] sc1
	v_mov_b32_e32 v5, 0x5000
	global_load_dword v6, v5, s[6:7] sc1
	s_waitcnt vmcnt(0)
	v_readfirstlane_b32 s9, v3
	v_readfirstlane_b32 s4, v6
	s_nop 3
	s_cmp_ge_u32 s9, s5
	s_cselect_b32 s9, 1, 0
	s_cmp_ge_u32 s4, s86
	s_cselect_b32 s4, 1, 0
	s_and_b32 s9, s9, s4
	s_cmp_lg_u32 s9, 0
	s_cbranch_scc1 .Lls9_ok
	s_sleep 1
	s_add_i32 s8, s8, 1
	s_cmp_lt_u32 s8, 0x20000
	s_cbranch_scc1 .Lls9_spin
.Lls9_ok:
	s_waitcnt vmcnt(0)
.LBB0_1288:
	s_or_b64 exec, exec, s[0:1]
	s_waitcnt lgkmcnt(0)
	s_barrier

; #define SEAM(k) do { if (IN(k) && IN((k) + 1)) xcd_barrier(bar); } while (0)
; __global__ void __launch_bounds__(NWAVES * 64, 2) mega_fwd(Args args) {
;     ...
;     SEAM(10);
;     if (IN(11)) { pg8::Gemm g{ACT, W2d, M, DM, FF, 64, FF, 0, 0, 1, (size_t)256 * 64 * 2, (size_t)(FF / 64) * 256 * 64 * 2}; pg8::StaticOrder S; S.init(M, DM, 1, G, bx);
;         pg8::EpiResid<true> E{nullptr, XB, ss3, 0.5f}; pg8::gemm_phase<pg8::EpiResid<true>, true>(lds, g, S, E); }
.LBB0_1327:
	s_cmp_gt_i32 s85, 11
	s_cselect_b64 s[2:3], -1, 0
	s_and_b64 s[0:1], s[0:1], s[2:3]
	v_readlane_b32 s48, v252, 22
	s_andn2_b64 vcc, exec, s[0:1]
	v_readlane_b32 s49, v252, 23
	s_cbranch_vccnz .LBB0_1381
	s_waitcnt vmcnt(0)
	s_waitcnt vmcnt(0) lgkmcnt(0)
	s_barrier
	s_and_saveexec_b64 s[0:1], s[74:75]
	s_cbranch_execz .LBB0_1380
	buffer_inv sc1
	s_and_b32 s4, s88, 7
	s_lshl_b32 s4, s4, 3
	s_bfe_u32 s5, s88, 0x30003
	s_or_b32 s4, s4, s5
	s_lshl_b32 s4, s4, 8
	s_add_u32 s6, s66, 0xfd09000
	s_addc_u32 s7, s67, 0
	v_mov_b32_e32 v1, s4
	v_mov_b32_e32 v2, 1
	global_atomic_add v1, v2, s[6:7]
	s_movk_i32 s5, 20
	s_mov_b32 s8, 0
.Lls10_spin:
	global_load_dword v3, v1, s[6:7] sc1
	s_waitcnt vmcnt(0)
	v_readfirstlane_b32 s9, v3
	s_nop 3
	s_cmp_ge_u32 s9, s5
	s_cbranch_scc1 .Lls10_ok
	s_sleep 1
	s_add_i32 s8, s8, 1
	s_cmp_lt_u32 s8, 0x20000
	s_cbranch_scc1 .Lls10_spin
.Lls10_ok:
	s_waitcnt vmcnt(0)
.LBB0_1380:
	s_or_b64 exec, exec, s[0:1]
	s_waitcnt lgkmcnt(0)
	s_barrier

; #define SEAM(k) do { if (IN(k) && IN((k) + 1)) xcd_barrier(bar); } while (0)
; __global__ void __launch_bounds__(NWAVES * 64, 2) mega_fwd(Args args) {
;     ...
;     SEAM(11);
;     if (IN(12)) { pg8::StaticOrder S; S.init(M, DM, 1, G, bx);
;         { pg8::Gemm g{XB, Wpg, M, DM, DM, DM, DM, 0, 0, 1}; pg8::EpiPle2 E{ss3, PTMP, XB, out}; pg8::gemm_phase<pg8::EpiPle2, true>(lds, g, S, E); } }
.LBB0_1428:
	s_cmp_gt_i32 s85, 12
	s_cselect_b64 s[2:3], -1, 0
	s_and_b64 s[0:1], s[0:1], s[2:3]
	s_andn2_b64 vcc, exec, s[0:1]
	s_cbranch_vccnz .LBB0_1482
	s_waitcnt vmcnt(0)
	s_waitcnt vmcnt(0) lgkmcnt(0)
	s_barrier
	s_and_saveexec_b64 s[0:1], s[74:75]
	s_cbranch_execz .LBB0_1481
	buffer_inv sc1
	s_and_b32 s4, s88, 7
	s_lshl_b32 s4, s4, 3
	s_bfe_u32 s5, s88, 0x30003
	s_or_b32 s4, s4, s5
	s_lshl_b32 s4, s4, 8
	s_add_u32 s6, s66, 0xfd09000
	s_addc_u32 s7, s67, 0
	v_mov_b32_e32 v1, s4
	v_mov_b32_e32 v2, 1
	global_atomic_add v1, v2, s[6:7]
	s_movk_i32 s5, 24
	s_mov_b32 s8, 0
.Lls11_spin:
	global_load_dword v3, v1, s[6:7] sc1
	s_waitcnt vmcnt(0)
	v_readfirstlane_b32 s9, v3
	s_nop 3
	s_cmp_ge_u32 s9, s5
	s_cbranch_scc1 .Lls11_ok
	s_sleep 1
	s_add_i32 s8, s8, 1
	s_cmp_lt_u32 s8, 0x20000
	s_cbranch_scc1 .Lls11_spin
.Lls11_ok:
	s_waitcnt vmcnt(0)
.LBB0_1481:
	s_or_b64 exec, exec, s[0:1]
	s_waitcnt lgkmcnt(0)
	s_barrier
